# attention PV: the first MFMA group waits per fragment pair (lgkmcnt 14/12/10/8) instead of for all eight V reads
# speedup vs baseline: 1.0059x; 1.0059x over previous
; #define SBAR() __builtin_amdgcn_sched_barrier(0)
; #define VF_WAIT(N) do { asm volatile("s_waitcnt lgkmcnt(" #N ")" ::: "memory"); SBAR(); } while (0)
; __device__ __forceinline__ void pv8(f32x16* o, int vb, bf16x8 pa0, bf16x8 pa1, bf16x8 pa2, bf16x8 pa3) {
;   VFrag fa, fb; const int vb2 = vb + 16384;
;   vf_read<0>(fa, vb);
;   vf_read<1>(fb, vb);  VF_WAIT(8); vf_mma(o[0], fa, pa0, pa1, pa2, pa3); SBAR();
;   vf_read<2>(fa, vb);  VF_WAIT(8); vf_mma(o[1], fb, pa0, pa1, pa2, pa3); SBAR();
;   vf_read<3>(fb, vb);  VF_WAIT(8); vf_mma(o[2], fa, pa0, pa1, pa2, pa3); SBAR();
.LBB0_363:
	v_lshl_add_u32 v220, s11, 15, v223
	ds_read_b64_tr_b16 v[144:145], v220 offset:0
	ds_read_b64_tr_b16 v[146:147], v220 offset:0x800
	ds_read_b64_tr_b16 v[148:149], v220 offset:0x1000
	ds_read_b64_tr_b16 v[150:151], v220 offset:0x1800
	ds_read_b64_tr_b16 v[152:153], v220 offset:0x2000
	ds_read_b64_tr_b16 v[154:155], v220 offset:0x2800
	ds_read_b64_tr_b16 v[156:157], v220 offset:0x3000
	ds_read_b64_tr_b16 v[158:159], v220 offset:0x3800
	ds_read_b64_tr_b16 v[194:195], v220 offset:0x200
	ds_read_b64_tr_b16 v[196:197], v220 offset:0xa00
	ds_read_b64_tr_b16 v[214:215], v220 offset:0x1200
	ds_read_b64_tr_b16 v[216:217], v220 offset:0x1a00
	ds_read_b64_tr_b16 v[228:229], v220 offset:0x2200
	ds_read_b64_tr_b16 v[230:231], v220 offset:0x2a00
	ds_read_b64_tr_b16 v[232:233], v220 offset:0x3200
	ds_read_b64_tr_b16 v[234:235], v220 offset:0x3a00
	v_add_u32_e32 v221, 0x4000, v220
	s_waitcnt lgkmcnt(14)
	v_mfma_f32_32x32x16_bf16 v[112:127], v[128:131], v[144:147], v[112:127]
	s_waitcnt lgkmcnt(12)
	v_mfma_f32_32x32x16_bf16 v[112:127], v[132:135], v[148:151], v[112:127]
	s_waitcnt lgkmcnt(10)
	v_mfma_f32_32x32x16_bf16 v[112:127], v[136:139], v[152:155], v[112:127]
	s_waitcnt lgkmcnt(8)
	v_mfma_f32_32x32x16_bf16 v[112:127], v[140:143], v[156:159], v[112:127]
	ds_read_b64_tr_b16 v[144:145], v220 offset:0x400
	ds_read_b64_tr_b16 v[146:147], v220 offset:0xc00
	ds_read_b64_tr_b16 v[148:149], v220 offset:0x1400
	ds_read_b64_tr_b16 v[150:151], v220 offset:0x1c00
	ds_read_b64_tr_b16 v[152:153], v220 offset:0x2400
	ds_read_b64_tr_b16 v[154:155], v220 offset:0x2c00
	ds_read_b64_tr_b16 v[156:157], v220 offset:0x3400
	ds_read_b64_tr_b16 v[158:159], v220 offset:0x3c00
	s_waitcnt lgkmcnt(8)
	v_mfma_f32_32x32x16_bf16 v[96:111], v[128:131], v[194:197], v[96:111]
	v_mfma_f32_32x32x16_bf16 v[96:111], v[132:135], v[214:217], v[96:111]
	v_mfma_f32_32x32x16_bf16 v[96:111], v[136:139], v[228:231], v[96:111]
	v_mfma_f32_32x32x16_bf16 v[96:111], v[140:143], v[232:235], v[96:111]
	ds_read_b64_tr_b16 v[194:195], v220 offset:0x600
	ds_read_b64_tr_b16 v[196:197], v220 offset:0xe00
	ds_read_b64_tr_b16 v[214:215], v220 offset:0x1600
	ds_read_b64_tr_b16 v[216:217], v220 offset:0x1e00
	ds_read_b64_tr_b16 v[228:229], v220 offset:0x2600
	ds_read_b64_tr_b16 v[230:231], v220 offset:0x2e00
	ds_read_b64_tr_b16 v[232:233], v220 offset:0x3600
	ds_read_b64_tr_b16 v[234:235], v220 offset:0x3e00
	s_cbranch_vccnz .Lp0_nodma
	s_lshl_b32 s12, s9, 15
	s_add_i32 s12, s12, s7
	s_mov_b32 s13, m0
	s_mov_b32 m0, s12
	s_nop 0
	global_load_lds_dwordx4 v204, s[38:39]
	s_add_i32 s24, s12, 0x400
	s_mov_b32 m0, s24
	s_nop 0
	global_load_lds_dwordx4 v206, s[38:39]
	s_add_i32 s24, s12, 0x800
	s_mov_b32 m0, s24
	s_nop 0
	global_load_lds_dwordx4 v208, s[38:39]
	s_add_i32 s24, s12, 0xc00
	s_mov_b32 m0, s24
	s_nop 0
	global_load_lds_dwordx4 v210, s[38:39]
	s_mov_b32 m0, s13

; #define SBAR() __builtin_amdgcn_sched_barrier(0)
; #define VF_WAIT(N) do { asm volatile("s_waitcnt lgkmcnt(" #N ")" ::: "memory"); SBAR(); } while (0)
; __device__ __forceinline__ void pv8(f32x16* o, int vb, bf16x8 pa0, bf16x8 pa1, bf16x8 pa2, bf16x8 pa3) {
;   VFrag fa, fb; const int vb2 = vb + 16384;
;   vf_read<0>(fa, vb);
;   vf_read<1>(fb, vb);  VF_WAIT(8); vf_mma(o[0], fa, pa0, pa1, pa2, pa3); SBAR();
;   vf_read<2>(fa, vb);  VF_WAIT(8); vf_mma(o[1], fb, pa0, pa1, pa2, pa3); SBAR();
;   vf_read<3>(fb, vb);  VF_WAIT(8); vf_mma(o[2], fa, pa0, pa1, pa2, pa3); SBAR();
.LBB0_396:
	v_lshl_add_u32 v231, s10, 15, v226
	ds_read_b64_tr_b16 v[144:145], v231 offset:0
	ds_read_b64_tr_b16 v[146:147], v231 offset:0x800
	ds_read_b64_tr_b16 v[148:149], v231 offset:0x1000
	ds_read_b64_tr_b16 v[150:151], v231 offset:0x1800
	ds_read_b64_tr_b16 v[152:153], v231 offset:0x2000
	ds_read_b64_tr_b16 v[154:155], v231 offset:0x2800
	ds_read_b64_tr_b16 v[156:157], v231 offset:0x3000
	ds_read_b64_tr_b16 v[158:159], v231 offset:0x3800
	ds_read_b64_tr_b16 v[194:195], v231 offset:0x200
	ds_read_b64_tr_b16 v[196:197], v231 offset:0xa00
	ds_read_b64_tr_b16 v[214:215], v231 offset:0x1200
	ds_read_b64_tr_b16 v[216:217], v231 offset:0x1a00
	ds_read_b64_tr_b16 v[220:221], v231 offset:0x2200
	ds_read_b64_tr_b16 v[222:223], v231 offset:0x2a00
	ds_read_b64_tr_b16 v[232:233], v231 offset:0x3200
	ds_read_b64_tr_b16 v[234:235], v231 offset:0x3a00
	v_add_u32_e32 v236, 0x4000, v231
	s_waitcnt lgkmcnt(14)
	v_mfma_f32_32x32x16_bf16 v[16:31], v[128:131], v[144:147], v[16:31]
	s_waitcnt lgkmcnt(12)
	v_mfma_f32_32x32x16_bf16 v[16:31], v[132:135], v[148:151], v[16:31]
	s_waitcnt lgkmcnt(10)
	v_mfma_f32_32x32x16_bf16 v[16:31], v[136:139], v[152:155], v[16:31]
	s_waitcnt lgkmcnt(8)
	v_mfma_f32_32x32x16_bf16 v[16:31], v[140:143], v[156:159], v[16:31]
	ds_read_b64_tr_b16 v[144:145], v231 offset:0x400
	ds_read_b64_tr_b16 v[146:147], v231 offset:0xc00
	ds_read_b64_tr_b16 v[148:149], v231 offset:0x1400
	ds_read_b64_tr_b16 v[150:151], v231 offset:0x1c00
	ds_read_b64_tr_b16 v[152:153], v231 offset:0x2400
	ds_read_b64_tr_b16 v[154:155], v231 offset:0x2c00
	ds_read_b64_tr_b16 v[156:157], v231 offset:0x3400
	ds_read_b64_tr_b16 v[158:159], v231 offset:0x3c00
	s_waitcnt lgkmcnt(8)
	v_mfma_f32_32x32x16_bf16 v[32:47], v[128:131], v[194:197], v[32:47]
	v_mfma_f32_32x32x16_bf16 v[32:47], v[132:135], v[214:217], v[32:47]
	v_mfma_f32_32x32x16_bf16 v[32:47], v[136:139], v[220:223], v[32:47]
	v_mfma_f32_32x32x16_bf16 v[32:47], v[140:143], v[232:235], v[32:47]
	ds_read_b64_tr_b16 v[194:195], v231 offset:0x600
	ds_read_b64_tr_b16 v[196:197], v231 offset:0xe00
	ds_read_b64_tr_b16 v[214:215], v231 offset:0x1600
	ds_read_b64_tr_b16 v[216:217], v231 offset:0x1e00
	ds_read_b64_tr_b16 v[220:221], v231 offset:0x2600
	ds_read_b64_tr_b16 v[222:223], v231 offset:0x2e00
	ds_read_b64_tr_b16 v[232:233], v231 offset:0x3600
	ds_read_b64_tr_b16 v[234:235], v231 offset:0x3e00
	s_cbranch_vccnz .Lp1_nodma
	s_lshl_b32 s11, s7, 15
	s_add_i32 s11, s11, s5
	s_mov_b32 s12, m0
	s_mov_b32 m0, s11
	s_nop 0
	global_load_lds_dwordx4 v204, s[60:61]
	s_add_i32 s13, s11, 0x400
	s_mov_b32 m0, s13
	s_nop 0
	global_load_lds_dwordx4 v206, s[60:61]
	s_add_i32 s13, s11, 0x800
	s_mov_b32 m0, s13
	s_nop 0
	global_load_lds_dwordx4 v208, s[60:61]
	s_add_i32 s13, s11, 0xc00
	s_mov_b32 m0, s13
	s_nop 0
	global_load_lds_dwordx4 v210, s[60:61]
	s_mov_b32 m0, s12
